# speedup vs baseline: 1.0160x; 1.0046x over previous
.LBB0_193:
	s_nop 7
	v_max_f32_e32 v34, v17, v17
	v_max_f32_e32 v35, v16, v16
	v_max_f32_e32 v34, v35, v34
	v_max3_f32 v34, v34, v18, v19
	v_max3_f32 v34, v34, v20, v21
	v_max3_f32 v34, v34, v22, v23
	v_max3_f32 v34, v34, v24, v25
	v_max3_f32 v34, v34, v26, v27
	v_max3_f32 v34, v34, v28, v29
	v_max3_f32 v34, v34, v30, v31
	v_max3_f32 v34, v34, v0, v1
	v_max3_f32 v34, v34, v2, v3
	v_max3_f32 v34, v34, v4, v5
	v_max3_f32 v34, v34, v6, v7
	v_max3_f32 v34, v34, v8, v9
	v_max3_f32 v34, v34, v10, v11
	v_max3_f32 v34, v34, v12, v13
	v_max3_f32 v34, v34, v14, v15
	v_mov_b32_e32 v35, v34
	s_nop 1
	v_permlane32_swap_b32_e32 v34, v35
	v_max_f32_e32 v35, v35, v35
	v_max_f32_e32 v34, v34, v34
	v_max_f32_e32 v34, v34, v35
	v_add_f32_e32 v35, 0x7149f2ca, v34
	v_mul_f32_e32 v35, 0x3e000000, v35
	s_mov_b32 s8, 0x41800000
	v_cmp_ge_f32_e32 vcc, s8, v35
	s_cmp_eq_u64 vcc, exec
	s_cselect_b64 vcc, -1, 0
	v_cmp_lt_i32_e64 s[8:9], 3, v32
	s_and_saveexec_b64 s[10:11], s[8:9]
	s_setprio 1
	s_or_b64 exec, exec, s[10:11]
	v_max_f32_e32 v34, 0xf149f2ca, v34
	v_mov_b32_e32 v32, 0xf149f2ca
	v_cndmask_b32_e32 v163, v34, v32, vcc
	v_mul_f32_e32 v32, 0xbe38aa3b, v163
	v_fmamk_f32 v16, v16, 0x3e38aa3b, v32
	v_exp_f32_e32 v188, v16
	v_sub_f32_e32 v16, 0xf149f2ca, v34
	v_mul_f32_e32 v16, 0x3e38aa3b, v16
	v_fmamk_f32 v17, v17, 0x3e38aa3b, v32
	v_fmamk_f32 v18, v18, 0x3e38aa3b, v32
	v_fmamk_f32 v19, v19, 0x3e38aa3b, v32
	v_fmamk_f32 v20, v20, 0x3e38aa3b, v32
	v_fmamk_f32 v21, v21, 0x3e38aa3b, v32
	v_fmamk_f32 v22, v22, 0x3e38aa3b, v32
	v_fmamk_f32 v23, v23, 0x3e38aa3b, v32
	v_fmamk_f32 v24, v24, 0x3e38aa3b, v32
	v_fmamk_f32 v25, v25, 0x3e38aa3b, v32
	v_fmamk_f32 v26, v26, 0x3e38aa3b, v32
	v_fmamk_f32 v27, v27, 0x3e38aa3b, v32
	v_fmamk_f32 v28, v28, 0x3e38aa3b, v32
	v_fmamk_f32 v29, v29, 0x3e38aa3b, v32
	v_fmamk_f32 v30, v30, 0x3e38aa3b, v32
	v_fmamk_f32 v31, v31, 0x3e38aa3b, v32
	v_exp_f32_e32 v16, v16
	v_exp_f32_e32 v190, v17
	v_exp_f32_e32 v186, v18
	v_exp_f32_e32 v189, v19
	v_exp_f32_e32 v184, v20
	v_exp_f32_e32 v187, v21
	v_exp_f32_e32 v183, v22
	v_exp_f32_e32 v185, v23
	v_exp_f32_e32 v171, v24
	v_exp_f32_e32 v180, v25
	v_exp_f32_e32 v170, v26
	v_exp_f32_e32 v172, v27
	v_exp_f32_e32 v169, v28
	v_exp_f32_e32 v182, v29
	v_exp_f32_e32 v173, v30
	v_exp_f32_e32 v181, v31
	v_pk_fma_f32 v[138:139], v[2:3], s[82:83], v[32:33] op_sel_hi:[1,0,0]
	v_pk_fma_f32 v[140:141], v[0:1], s[82:83], v[32:33] op_sel_hi:[1,0,0]
	v_and_b32_e32 v0, 0x3fffffc0, v143
	v_lshlrev_b32_e32 v2, 6, v143
	v_lshlrev_b32_e32 v0, 2, v0
	v_and_b32_e32 v1, 0x78, v33
	v_and_b32_e32 v2, 0x400, v2
	v_lshlrev_b32_e32 v3, 8, v146
	s_add_i32 s8, s3, 2
	v_cndmask_b32_e64 v149, v16, 1.0, vcc
	v_pk_fma_f32 v[86:87], v[14:15], s[82:83], v[32:33] op_sel_hi:[1,0,0]
	v_pk_fma_f32 v[88:89], v[12:13], s[82:83], v[32:33] op_sel_hi:[1,0,0]
	v_pk_fma_f32 v[90:91], v[10:11], s[82:83], v[32:33] op_sel_hi:[1,0,0]
	v_pk_fma_f32 v[94:95], v[8:9], s[82:83], v[32:33] op_sel_hi:[1,0,0]
	v_pk_fma_f32 v[134:135], v[6:7], s[82:83], v[32:33] op_sel_hi:[1,0,0]
	v_pk_fma_f32 v[136:137], v[4:5], s[82:83], v[32:33] op_sel_hi:[1,0,0]
	v_or3_b32 v151, v1, v2, v3
	s_cmp_ge_i32 s8, s77
	v_cmp_gt_u32_e64 s[8:9], 32, v144
	v_lshl_add_u32 v147, v148, 2, v0
	v_lshl_add_u32 v145, v157, 2, v0
	s_cbranch_scc1 .LBB0_221
	v_mov_b32_e32 v150, 0
	s_mov_b64 s[92:93], s[14:15]
	s_mov_b64 s[14:15], s[12:13]
	s_mov_b32 s12, s71
	s_mov_b32 s71, s46
	s_mov_b32 s70, s37
	s_mov_b32 s10, 2
	v_subrev_u32_e32 v128, s2, v157
	s_mov_b32 s2, 0
	s_sub_i32 s18, 0, s77
	s_add_i32 s19, s3, 3
	s_mov_b32 s86, 1
	v_mov_b32_e32 v166, v144
	v_mov_b32_e32 v16, 0
	v_mov_b32_e32 v17, v150
	v_mov_b32_e32 v18, v150
	v_mov_b32_e32 v19, v150
	v_mov_b32_e32 v20, v150
	v_mov_b32_e32 v21, v150
	v_mov_b32_e32 v22, v150
	v_mov_b32_e32 v23, v150
	v_mov_b32_e32 v24, v150
	v_mov_b32_e32 v25, v150
	v_mov_b32_e32 v26, v150
	v_mov_b32_e32 v27, v150
	v_mov_b32_e32 v28, v150
	v_mov_b32_e32 v29, v150
	v_mov_b32_e32 v30, v150
	v_mov_b32_e32 v31, v150
	v_mov_b32_e32 v0, 0
	v_mov_b32_e32 v1, v150
	v_mov_b32_e32 v2, v150
	v_mov_b32_e32 v3, v150
	v_mov_b32_e32 v4, v150
	v_mov_b32_e32 v5, v150
	v_mov_b32_e32 v6, v150
	v_mov_b32_e32 v7, v150
	v_mov_b32_e32 v8, v150
	v_mov_b32_e32 v9, v150
	v_mov_b32_e32 v10, v150
	v_mov_b32_e32 v11, v150
	v_mov_b32_e32 v12, v150
	v_mov_b32_e32 v13, v150
	v_mov_b32_e32 v14, v150
	v_mov_b32_e32 v15, v150
	v_add_u32_e32 v248, s78, v158
	v_add_u32_e32 v248, 0xc0, v248
	v_lshlrev_b32_e32 v248, 11, v248
	v_lshl_or_b32 v248, v159, 1, v248
	v_add_u32_e32 v249, s78, v166
	v_add_u32_e32 v249, 0xc0, v249
	v_lshlrev_b32_e32 v249, 2, v249

.LBB0_199:
	s_cmp_lt_i32 s19, s77
	s_cselect_b64 s[22:23], -1, 0
	s_cmp_ge_i32 s19, s77
	s_cbranch_scc1 .LBB0_201
	global_load_dwordx4 v[112:115], v248, s[42:43]
	global_load_dwordx4 v[116:119], v248, s[40:41]
	global_load_dword v160, v249, s[38:39]

.LBB0_209:
	s_add_i32 s36, s19, 1
	s_cmp_ge_i32 s36, s77
	s_cbranch_scc1 .LBB0_211
	v_add_u32_e32 v250, 0x20000, v248
	global_load_dwordx4 v[120:123], v250, s[42:43]
	global_load_dwordx4 v[124:127], v250, s[40:41]
	global_load_dword v165, v249, s[38:39] offset:256

.LBB0_219:
	v_cndmask_b32_e64 v163, v32, v136, s[10:11]
	v_mul_f32_e32 v32, 0xbe38aa3b, v163
	v_fmamk_f32 v34, v80, 0x3e38aa3b, v32
	v_fmamk_f32 v35, v81, 0x3e38aa3b, v32
	v_fmamk_f32 v36, v82, 0x3e38aa3b, v32
	v_fmamk_f32 v37, v83, 0x3e38aa3b, v32
	v_fmamk_f32 v38, v84, 0x3e38aa3b, v32
	v_fmamk_f32 v39, v85, 0x3e38aa3b, v32
	v_fmamk_f32 v40, v86, 0x3e38aa3b, v32
	v_fmamk_f32 v41, v87, 0x3e38aa3b, v32
	v_fmamk_f32 v42, v88, 0x3e38aa3b, v32
	v_fmamk_f32 v43, v89, 0x3e38aa3b, v32
	v_fmamk_f32 v44, v90, 0x3e38aa3b, v32
	v_fmamk_f32 v45, v91, 0x3e38aa3b, v32
	v_fmamk_f32 v46, v92, 0x3e38aa3b, v32
	v_fmamk_f32 v47, v93, 0x3e38aa3b, v32
	v_fmamk_f32 v50, v94, 0x3e38aa3b, v32
	v_fmamk_f32 v51, v95, 0x3e38aa3b, v32
	v_exp_f32_e32 v188, v34
	v_exp_f32_e32 v190, v35
	v_exp_f32_e32 v186, v36
	v_exp_f32_e32 v189, v37
	v_exp_f32_e32 v184, v38
	v_exp_f32_e32 v187, v39
	v_exp_f32_e32 v183, v40
	v_exp_f32_e32 v185, v41
	v_exp_f32_e32 v171, v42
	v_exp_f32_e32 v180, v43
	v_exp_f32_e32 v170, v44
	v_exp_f32_e32 v172, v45
	v_exp_f32_e32 v169, v46
	v_exp_f32_e32 v182, v47
	v_exp_f32_e32 v173, v50
	v_exp_f32_e32 v181, v51
	v_pk_fma_f32 v[86:87], v[78:79], s[82:83], v[32:33] op_sel_hi:[1,0,0]
	v_pk_fma_f32 v[88:89], v[76:77], s[82:83], v[32:33] op_sel_hi:[1,0,0]
	v_pk_fma_f32 v[90:91], v[74:75], s[82:83], v[32:33] op_sel_hi:[1,0,0]
	v_pk_fma_f32 v[94:95], v[72:73], s[82:83], v[32:33] op_sel_hi:[1,0,0]
	v_pk_fma_f32 v[134:135], v[70:71], s[82:83], v[32:33] op_sel_hi:[1,0,0]
	v_pk_fma_f32 v[136:137], v[68:69], s[82:83], v[32:33] op_sel_hi:[1,0,0]
	v_pk_fma_f32 v[138:139], v[66:67], s[82:83], v[32:33] op_sel_hi:[1,0,0]
	v_pk_fma_f32 v[140:141], v[64:65], s[82:83], v[32:33] op_sel_hi:[1,0,0]
	v_add_f32_e32 v32, v167, v168
	v_fmac_f32_e32 v32, v149, v150
	v_add_f32_e32 v150, v48, v49
	s_add_i32 s19, s19, 2
	v_fmac_f32_e32 v150, v32, v191
	v_add_u32_e32 v128, 0x80, v128
	v_add_u32_e32 v166, 0x80, v166
	s_cmp_ge_i32 s36, s77
	v_add_u32_e32 v158, 0x80, v158
	v_add_u32_e32 v248, 0x40000, v248
	v_add_u32_e32 v249, 0x200, v249
	s_waitcnt lgkmcnt(0)
	s_barrier
	s_cbranch_scc1 .LBB0_222
	s_mov_b32 s10, s86
	s_mov_b32 s86, s2
	s_mov_b32 s2, s79
	v_mov_b32_e32 v149, v33
	s_branch .LBB0_197
